# slot fusion v3: fp8 table conversion of both layers removed from prep and overlapped with GEMM work (layer 0 in the slot-0 in-proj, layer 1 in phase 6), CU mates alternate
# baseline (speedup 1.0000x reference)
; DEVI void convert_chunk_fp8(const float* __restrict__ src, unsigned char* __restrict__ dst, float scale, int tid) {
;   int o = tid * 16;
;   uint4 r;
;   unsigned rr[4];
; #pragma unroll
;   for (int q = 0; q < 4; ++q) {
;     float4 a = *reinterpret_cast<const float4*>(src + o + q * 4);
;     int p = __builtin_amdgcn_cvt_pk_fp8_f32(a.x * scale, a.y * scale, 0, false);
;     p = __builtin_amdgcn_cvt_pk_fp8_f32(a.z * scale, a.w * scale, p, true);
;     rr[q] = (unsigned)p;
;   }
;   r = make_uint4(rr[0], rr[1], rr[2], rr[3]);
;   *reinterpret_cast<uint4*>(dst + o) = r;
; }
; DEVI void phase_prep(const Params& P, int l, char* smem) {
;     ...
;     } else if (id < C2) {
;       int q = id - C1;
;       convert_chunk_fp8(P.in[27] + (long)l * 16777216 + (long)q * 4096, (unsigned char*)(ws + O_VTB) + (long)q * 4096, V_SCALE, tid);
.LBB0_17:
	s_branch .LBB0_19

; #define LND asm volatile("" : "+s"(l), "+s"(pass))
; DEVI void convert_chunk_fp8(const float* __restrict__ src, unsigned char* __restrict__ dst, float scale, int tid) {
;   int o = tid * 16;
;   uint4 r;
;   unsigned rr[4];
; #pragma unroll
;   for (int q = 0; q < 4; ++q) {
;     float4 a = *reinterpret_cast<const float4*>(src + o + q * 4);
;     int p = __builtin_amdgcn_cvt_pk_fp8_f32(a.x * scale, a.y * scale, 0, false);
;     p = __builtin_amdgcn_cvt_pk_fp8_f32(a.z * scale, a.w * scale, p, true);
;     rr[q] = (unsigned)p;
;   }
;   r = make_uint4(rr[0], rr[1], rr[2], rr[3]);
;   *reinterpret_cast<uint4*>(dst + o) = r;
; }
; __global__ void __launch_bounds__(256, 2) fwd_megakernel(Params P) {
;     ...
;           if (it < 2) { pass = __builtin_amdgcn_readfirstlane(it); LND; phase_inproj(P, l, pass, smem); }
.LBB0_277:
	s_andn2_b64 vcc, exec, s[40:41]
	s_cbranch_vccnz .LBB0_298
	s_andn2_b64 vcc, exec, s[6:7]
	s_cbranch_vccnz .LBB0_297
	v_readlane_b32 s60, v252, 36
	s_cmp_lg_u32 s2, 0
	s_cbranch_scc1 .Ltb_skip_c
	s_cmp_lg_u32 s60, 0
	s_cbranch_scc1 .Ltb_skip_c
	v_readlane_b32 s60, v252, 32
	s_cmpk_lt_u32 s60, 0x100
	s_cbranch_scc0 .Ltb_skip_c
	v_readlane_b32 s54, v253, 22
	v_readlane_b32 s55, v253, 23
	v_readlane_b32 s56, v253, 24
	v_readlane_b32 s57, v253, 25
	s_lshl_b32 s61, s2, 26
	s_add_u32 s54, s54, s61
	s_addc_u32 s55, s55, 0
	s_add_u32 s56, s56, s61
	s_addc_u32 s57, s57, 0
	v_lshlrev_b32_e32 v248, 6, v93
	v_lshlrev_b32_e32 v250, 4, v93
	v_mov_b32_e32 v251, 0
	v_lshl_add_u64 v[250:251], v[64:65], 0, v[250:251]
.Ltb_loop_c:
	s_lshl_b32 s61, s60, 14
	s_add_u32 s42, s54, s61
	s_addc_u32 s43, s55, 0
	s_add_u32 s44, s56, s61
	s_addc_u32 s45, s57, 0
	global_load_dwordx4 v[208:211], v248, s[42:43]
	global_load_dwordx4 v[212:215], v248, s[42:43] offset:16
	global_load_dwordx4 v[216:219], v248, s[42:43] offset:32
	global_load_dwordx4 v[220:223], v248, s[42:43] offset:48
	global_load_dwordx4 v[224:227], v248, s[44:45]
	global_load_dwordx4 v[228:231], v248, s[44:45] offset:16
	global_load_dwordx4 v[232:235], v248, s[44:45] offset:32
	global_load_dwordx4 v[236:239], v248, s[44:45] offset:48
	s_lshl_b32 s61, s60, 12
	s_add_u32 s58, s61, 0x2500000
	s_mov_b32 s59, 0
	v_lshl_add_u64 v[202:203], v[250:251], 0, s[58:59]
	s_add_u32 s58, s61, 0x4500000
	v_lshl_add_u64 v[204:205], v[250:251], 0, s[58:59]
	s_waitcnt vmcnt(4)
	v_mul_f32_e32 v208, 0x42800000, v208
	v_mul_f32_e32 v209, 0x42800000, v209
	v_mul_f32_e32 v210, 0x42800000, v210
	v_mul_f32_e32 v211, 0x42800000, v211
	v_mul_f32_e32 v212, 0x42800000, v212
	v_mul_f32_e32 v213, 0x42800000, v213
	v_mul_f32_e32 v214, 0x42800000, v214
	v_mul_f32_e32 v215, 0x42800000, v215
	v_mul_f32_e32 v216, 0x42800000, v216
	v_mul_f32_e32 v217, 0x42800000, v217
	v_mul_f32_e32 v218, 0x42800000, v218
	v_mul_f32_e32 v219, 0x42800000, v219
	v_mul_f32_e32 v220, 0x42800000, v220
	v_mul_f32_e32 v221, 0x42800000, v221
	v_mul_f32_e32 v222, 0x42800000, v222
	v_mul_f32_e32 v223, 0x42800000, v223
	v_mov_b32_e32 v240, v89
	v_mov_b32_e32 v241, v89
	v_mov_b32_e32 v242, v89
	v_mov_b32_e32 v243, v89
	v_cvt_pk_fp8_f32 v240, v208, v209
	v_cvt_pk_fp8_f32 v241, v212, v213
	v_cvt_pk_fp8_f32 v242, v216, v217
	v_cvt_pk_fp8_f32 v243, v220, v221
	v_cvt_pk_fp8_f32 v240, v210, v211 op_sel:[0,0,1]
	v_cvt_pk_fp8_f32 v241, v214, v215 op_sel:[0,0,1]
	v_cvt_pk_fp8_f32 v242, v218, v219 op_sel:[0,0,1]
	v_cvt_pk_fp8_f32 v243, v222, v223 op_sel:[0,0,1]
	global_store_dwordx4 v[202:203], v[240:243], off
	s_waitcnt vmcnt(1)
	v_mul_f32_e32 v224, 0x41000000, v224
	v_mul_f32_e32 v225, 0x41000000, v225
	v_mul_f32_e32 v226, 0x41000000, v226
	v_mul_f32_e32 v227, 0x41000000, v227
	v_mul_f32_e32 v228, 0x41000000, v228
	v_mul_f32_e32 v229, 0x41000000, v229
	v_mul_f32_e32 v230, 0x41000000, v230
	v_mul_f32_e32 v231, 0x41000000, v231
	v_mul_f32_e32 v232, 0x41000000, v232
	v_mul_f32_e32 v233, 0x41000000, v233
	v_mul_f32_e32 v234, 0x41000000, v234
	v_mul_f32_e32 v235, 0x41000000, v235
	v_mul_f32_e32 v236, 0x41000000, v236
	v_mul_f32_e32 v237, 0x41000000, v237
	v_mul_f32_e32 v238, 0x41000000, v238
	v_mul_f32_e32 v239, 0x41000000, v239
	v_mov_b32_e32 v244, v89
	v_mov_b32_e32 v245, v89
	v_mov_b32_e32 v246, v89
	v_mov_b32_e32 v247, v89
	v_cvt_pk_fp8_f32 v244, v224, v225
	v_cvt_pk_fp8_f32 v245, v228, v229
	v_cvt_pk_fp8_f32 v246, v232, v233
	v_cvt_pk_fp8_f32 v247, v236, v237
	v_cvt_pk_fp8_f32 v244, v226, v227 op_sel:[0,0,1]
	v_cvt_pk_fp8_f32 v245, v230, v231 op_sel:[0,0,1]
	v_cvt_pk_fp8_f32 v246, v234, v235 op_sel:[0,0,1]
	v_cvt_pk_fp8_f32 v247, v238, v239 op_sel:[0,0,1]
	global_store_dwordx4 v[204:205], v[244:247], off
	s_addk_i32 s60, 0x200
	s_cmpk_lt_u32 s60, 0x1000
	s_cbranch_scc1 .Ltb_loop_c
; DEVI char* wsp(const Params& P, size_t off) { asm volatile("" : "+s"(off)); return P.ws + off; }
; DEVI int ltid() { int t = threadIdx.x; asm volatile("" : "+v"(t)); return t; }
; #define ZERO_ACC(a) _Pragma("unroll") for (int m_ = 0; m_ < 4; ++m_) _Pragma("unroll") for (int n_ = 0; n_ < 4; ++n_) a[m_][n_] = f32x4{0.f, 0.f, 0.f, 0.f}
; DEVI void stage_tile(const bfu* __restrict__ g, int ld, int k0, char* lds, int tid) {
; #pragma unroll
;   for (int i = 0; i < 4; ++i) {
;     int b = tid * 16 + i * 4096;
;     int r = b >> 7, cp = (b >> 4) & 7, gc = cp ^ (r & 7);
;     __builtin_amdgcn_global_load_lds((const unsigned*)(g + (long)r * ld + k0 + gc * 8),
;                                      (unsigned*)(lds + b), 16, 0, 0);
;   }
; }
; DEVI void phase_inproj(const Params& P, int l, int pass, char* smem) {
;   const int tid = ltid();
;   const int ntok = pass ? 8192 : 8448, base = pass ? 8448 : 0;
;   const int nM = ntok / 128, nN = 96;
;   const bfu* xb = (const bfu*)wsp(P, O_XB) + (long)base * 1024;
;   const bfu* wT = (const bfu*)wsp(P, O_WIN);
;   bfu* z = (bfu*)wsp(P, O_Z);
;   const float* bin = P.in[7] + l * NCOL;
;   for (int id = blockIdx.x; id < nM * nN; id += gridDim.x) {
;     int pm, pn; tile_rc(id, nM, nN, pm, pn);
;     f32x4 acc[4][4]; ZERO_ACC(acc);
;     gemm_core(acc, xb + (long)pm * 128 * 1024, 1024, wT + (long)pn * 128 * 1024, 1024, 1024, smem, tid);
;     epi_store_bf16(acc, bin + pn * 128, z + (long)pm * 128 * NCOL + pn * 128, NCOL, smem, tid);
.Ltb_skip_c:
	s_mov_b32 s0, s51
	s_cmp_eq_u32 s0, 0
	s_cselect_b64 s[42:43], -1, 0
	s_and_b64 s[0:1], s[42:43], exec
	s_cselect_b32 s49, 0x42, 64
	s_mul_i32 s46, s49, 0x60
	v_readlane_b32 s50, v252, 32
	v_mov_b32_e32 v0, v93
	s_mov_b64 s[40:41], 0x6502000
	s_mov_b64 s[0:1], 0
	s_mov_b64 s[44:45], 0x8582000
	s_cmp_ge_i32 s50, s46
	s_cbranch_scc1 .LBB0_297
	v_lshlrev_b32_e32 v91, 4, v0
	v_add_u32_e32 v172, 0x2000, v91
	v_ashrrev_i32_e32 v14, 7, v172
	v_lshrrev_b32_e32 v1, 4, v0
	v_xor_b32_e32 v13, v14, v0
	v_add_u32_e32 v173, 0x3000, v91
	v_and_b32_e32 v25, 7, v0
	v_lshlrev_b32_e32 v13, 3, v13
	v_ashrrev_i32_e32 v20, 7, v173
	v_bitop3_b32 v1, v1, v25, 3 bitop3:0x6c
	v_bfe_u32 v7, v0, 4, 2
	v_and_b32_e32 v18, 56, v13
	v_xor_b32_e32 v13, v20, v0
	v_lshlrev_b32_e32 v174, 4, v1
	v_lshlrev_b32_e32 v1, 7, v0
	v_readlane_b32 s4, v254, 44
	v_lshlrev_b32_e32 v13, 3, v13
	v_and_b32_e32 v176, 0x2780, v1
	v_bitop3_b32 v1, v7, v25, 4 bitop3:0x36
	v_and_b32_e32 v24, 56, v13
	v_and_b32_e32 v13, 15, v0
	v_lshrrev_b32_e32 v19, 1, v0
	s_mov_b32 s4, 0x1ffffc0
	v_lshlrev_b32_e32 v177, 4, v1
	v_lshrrev_b32_e32 v1, 2, v0
	s_and_b64 s[42:43], s[42:43], exec
	v_and_or_b32 v13, v19, s4, v13
	v_and_b32_e32 v1, 12, v1
	s_mov_b32 s4, 0xfffffc0
	s_mul_i32 s42, s2, 0x3000
	v_and_or_b32 v1, v19, s4, v1
	s_movk_i32 s4, 0x110
	s_cselect_b32 s24, 0, 0x1080000
	s_ashr_i32 s43, s42, 31
	v_and_b32_e32 v106, 0x4f, v0
	v_mul_lo_u32 v1, v1, s4
	s_lshl_b64 s[42:43], s[42:43], 2
	v_readlane_b32 s14, v254, 54
	v_lshl_add_u32 v178, v106, 1, v1
	v_lshlrev_b32_e32 v1, 3, v0
	v_readlane_b32 s15, v254, 55
	s_add_u32 s47, s14, s42
	v_and_b32_e32 v26, 0x78, v1
	v_ashrrev_i32_e32 v1, 4, v0
	s_addc_u32 s48, s15, s43
	v_lshlrev_b32_e32 v175, 7, v13
	v_mul_lo_u32 v13, v1, s4
	v_mad_i64_i32 v[108:109], s[42:43], v1, s22, 0
	v_add_u32_e32 v1, 0x100, v0
	v_ashrrev_i32_e32 v1, 4, v1
	v_mul_lo_u32 v19, v1, s4
	v_mad_i64_i32 v[110:111], s[42:43], v1, s22, 0
	v_add_u32_e32 v1, 0x200, v0
	v_ashrrev_i32_e32 v1, 4, v1
	v_mul_lo_u32 v25, v1, s4
	v_mad_i64_i32 v[112:113], s[42:43], v1, s22, 0
	v_add_u32_e32 v1, 0x300, v0
	v_ashrrev_i32_e32 v1, 4, v1
	v_mul_lo_u32 v27, v1, s4
	v_mad_i64_i32 v[114:115], s[42:43], v1, s22, 0
	v_add_u32_e32 v1, 0x400, v0
	v_ashrrev_i32_e32 v1, 4, v1
	v_mul_lo_u32 v36, v1, s4
	v_mad_i64_i32 v[116:117], s[42:43], v1, s22, 0
	v_add_u32_e32 v1, 0x500, v0
	v_ashrrev_i32_e32 v1, 4, v1
	v_mul_lo_u32 v37, v1, s4
	v_mad_i64_i32 v[118:119], s[42:43], v1, s22, 0
	v_add_u32_e32 v1, 0x600, v0
	v_lshl_add_u64 v[2:3], v[64:65], 0, s[40:41]
	v_ashrrev_i32_e32 v1, 4, v1
	v_lshl_add_u64 v[100:101], v[2:3], 0, s[24:25]
	v_ashrrev_i32_e32 v2, 3, v0
	v_mul_lo_u32 v38, v1, s4
	v_mad_i64_i32 v[120:121], s[42:43], v1, s22, 0
	v_add_u32_e32 v1, 0x700, v0
	v_ashrrev_i32_e32 v3, 31, v2
	v_ashrrev_i32_e32 v1, 4, v1
	v_mul_lo_u32 v39, v1, s4
	v_mad_i64_i32 v[122:123], s[42:43], v1, s22, 0
	v_lshlrev_b64 v[28:29], 11, v[2:3]
	v_bitop3_b32 v1, v2, 7, v0 bitop3:0x48
	v_add_u32_e32 v107, 0x1000, v91
	v_lshl_add_u64 v[30:31], s[40:41], 0, v[28:29]
	v_lshlrev_b32_e32 v88, 4, v1
	v_xor_b32_e32 v6, v2, v0
	v_lshlrev_b64 v[4:5], 10, v[2:3]
	v_ashrrev_i32_e32 v8, 7, v107
	v_lshl_add_u64 v[2:3], v[30:31], 0, v[88:89]
	v_ashrrev_i32_e32 v9, 31, v8
	v_lshl_add_u64 v[2:3], v[2:3], 0, s[24:25]
	v_lshl_add_u64 v[124:125], v[86:87], 0, v[2:3]
	v_lshlrev_b64 v[2:3], 11, v[8:9]
	v_bitop3_b32 v1, v8, 7, v0 bitop3:0x48
	v_xor_b32_e32 v12, v8, v0
	v_lshlrev_b64 v[10:11], 10, v[8:9]
	v_lshl_add_u64 v[30:31], s[40:41], 0, v[2:3]
	v_lshlrev_b32_e32 v8, 4, v1
	v_mov_b32_e32 v9, v89
	v_lshl_add_u64 v[30:31], v[30:31], 0, v[8:9]
	v_ashrrev_i32_e32 v15, 31, v14
	v_lshl_add_u64 v[30:31], v[30:31], 0, s[24:25]
	v_lshl_add_u64 v[126:127], v[86:87], 0, v[30:31]
	v_lshlrev_b64 v[30:31], 11, v[14:15]
	v_bitop3_b32 v1, v14, 7, v0 bitop3:0x48
	v_lshlrev_b64 v[16:17], 10, v[14:15]
	v_lshl_add_u64 v[32:33], s[40:41], 0, v[30:31]
	v_lshlrev_b32_e32 v14, 4, v1
	v_mov_b32_e32 v15, v89
	v_lshl_add_u64 v[32:33], v[32:33], 0, v[14:15]
	v_ashrrev_i32_e32 v21, 31, v20
	v_lshl_add_u64 v[32:33], v[32:33], 0, s[24:25]
	v_lshl_add_u64 v[128:129], v[86:87], 0, v[32:33]
	v_lshlrev_b64 v[32:33], 11, v[20:21]
	v_bitop3_b32 v0, v20, 7, v0 bitop3:0x48
	v_lshl_add_u64 v[2:3], s[0:1], 0, v[2:3]
	s_add_i32 s49, s49, 0xffc0
	v_lshl_add_u64 v[34:35], s[40:41], 0, v[32:33]
	v_lshlrev_b32_e32 v0, 4, v0
	v_mov_b32_e32 v1, v89
	v_lshl_add_u64 v[2:3], v[2:3], 0, v[8:9]
	v_lshlrev_b64 v[22:23], 10, v[20:21]
	v_cvt_f32_ubyte0_e32 v179, s49
	v_lshl_add_u64 v[20:21], v[34:35], 0, v[0:1]
	v_lshl_add_u64 v[134:135], v[86:87], 0, v[2:3]
	v_lshl_add_u64 v[2:3], s[0:1], 0, v[30:31]
	v_rcp_iflag_f32_e32 v180, v179
	v_lshl_add_u64 v[20:21], v[20:21], 0, s[24:25]
	v_lshl_add_u64 v[2:3], v[2:3], 0, v[14:15]
	v_lshlrev_b32_e32 v6, 3, v6
	v_lshlrev_b32_e32 v12, 3, v12
	v_lshl_add_u64 v[130:131], v[86:87], 0, v[20:21]
	v_lshl_add_u64 v[20:21], s[0:1], 0, v[28:29]
	v_lshl_add_u64 v[136:137], v[86:87], 0, v[2:3]
	v_lshl_add_u64 v[2:3], s[0:1], 0, v[32:33]
	v_and_b32_e32 v6, 56, v6
	v_and_b32_e32 v12, 56, v12
	v_lshlrev_b32_e32 v7, 1, v26
	v_lshl_add_u64 v[20:21], v[20:21], 0, v[88:89]
	v_lshl_add_u64 v[0:1], v[2:3], 0, v[0:1]
	v_lshl_add_u64 v[102:103], v[64:65], 0, s[0:1]
	v_lshl_add_u64 v[104:105], v[64:65], 0, s[44:45]
	s_movk_i32 s37, 0x110
	v_lshl_add_u64 v[132:133], v[86:87], 0, v[20:21]
	v_lshl_add_u64 v[138:139], v[86:87], 0, v[0:1]
	v_lshlrev_b64 v[140:141], 1, v[4:5]
	v_lshlrev_b32_e32 v142, 1, v6
	v_lshlrev_b64 v[144:145], 1, v[10:11]
	v_lshlrev_b32_e32 v146, 1, v12
	v_lshlrev_b64 v[148:149], 1, v[16:17]
	v_lshlrev_b32_e32 v150, 1, v18
	v_lshlrev_b64 v[152:153], 1, v[22:23]
	v_lshlrev_b32_e32 v154, 1, v24
	v_lshlrev_b32_e32 v88, 1, v26
	v_add_u32_e32 v181, v7, v13
	v_add_u32_e32 v182, v7, v19
	v_add_u32_e32 v183, v7, v25
	v_add_u32_e32 v196, v7, v27
	v_add_u32_e32 v197, v7, v36
	v_add_u32_e32 v198, v7, v37
	v_add_u32_e32 v199, v7, v38
	v_add_u32_e32 v200, v7, v39
	s_mov_b32 s24, s50
	v_readlane_b32 s5, v254, 45
	v_readlane_b32 s6, v254, 46
	v_readlane_b32 s7, v254, 47
	v_readlane_b32 s8, v254, 48
	v_readlane_b32 s9, v254, 49
	v_readlane_b32 s10, v254, 50
	v_readlane_b32 s11, v254, 51
	v_readlane_b32 s12, v254, 52
	v_readlane_b32 s13, v254, 53
	v_readlane_b32 s16, v254, 56
	v_readlane_b32 s17, v254, 57
	v_readlane_b32 s18, v254, 58
	v_readlane_b32 s19, v254, 59
	v_add_u32_e32 v201, v140, v142
	v_add_u32_e32 v250, v144, v146
	v_add_u32_e32 v251, v148, v150
	v_add_u32_e32 v255, v152, v154
	v_readfirstlane_b32 s60, v100
	v_readfirstlane_b32 s61, v101
	v_readfirstlane_b32 s62, v102
	v_readfirstlane_b32 s63, v103
	s_branch .LBB0_282

; #define ZERO_ACC(a) _Pragma("unroll") for (int m_ = 0; m_ < 4; ++m_) _Pragma("unroll") for (int n_ = 0; n_ < 4; ++n_) a[m_][n_] = f32x4{0.f, 0.f, 0.f, 0.f}
; DEVI void convert_chunk_fp8(const float* __restrict__ src, unsigned char* __restrict__ dst, float scale, int tid) {
;   int o = tid * 16;
;   uint4 r;
;   unsigned rr[4];
; #pragma unroll
;   for (int q = 0; q < 4; ++q) {
;     float4 a = *reinterpret_cast<const float4*>(src + o + q * 4);
;     int p = __builtin_amdgcn_cvt_pk_fp8_f32(a.x * scale, a.y * scale, 0, false);
;     p = __builtin_amdgcn_cvt_pk_fp8_f32(a.z * scale, a.w * scale, p, true);
;     rr[q] = (unsigned)p;
;   }
;   r = make_uint4(rr[0], rr[1], rr[2], rr[3]);
;   *reinterpret_cast<uint4*>(dst + o) = r;
; }
; DEVI void phase_inproj(const Params& P, int l, int pass, char* smem) {
;     ...
;   for (int id = blockIdx.x; id < nM * nN; id += gridDim.x) {
;     int pm, pn; tile_rc(id, nM, nN, pm, pn);
;     f32x4 acc[4][4]; ZERO_ACC(acc);
;     gemm_core(acc, xb + (long)pm * 128 * 1024, 1024, wT + (long)pn * 128 * 1024, 1024, 1024, smem, tid);
;     epi_store_bf16(acc, bin + pn * 128, z + (long)pm * 128 * NCOL + pn * 128, NCOL, smem, tid);
;   }
.LBB0_297:
	s_mov_b32 s0, s2
	v_readlane_b32 s60, v252, 36
	s_cmp_lg_u32 s0, 0
	s_cbranch_scc1 .Ltb_skip_d
	s_cmp_lg_u32 s60, 0
	s_cbranch_scc1 .Ltb_skip_d
	v_readlane_b32 s60, v252, 32
	s_cmpk_lt_u32 s60, 0x100
	s_cbranch_scc1 .Ltb_skip_d
	v_readlane_b32 s54, v253, 22
	v_readlane_b32 s55, v253, 23
	v_readlane_b32 s56, v253, 24
	v_readlane_b32 s57, v253, 25
	s_lshl_b32 s61, s0, 26
	s_add_u32 s54, s54, s61
	s_addc_u32 s55, s55, 0
	s_add_u32 s56, s56, s61
	s_addc_u32 s57, s57, 0
	v_lshlrev_b32_e32 v248, 6, v93
	v_lshlrev_b32_e32 v250, 4, v93
	v_mov_b32_e32 v251, 0
	v_lshl_add_u64 v[250:251], v[64:65], 0, v[250:251]

; DEVI unsigned xb_add(unsigned* p, unsigned v) { return __hip_atomic_fetch_add(p, v, __ATOMIC_RELAXED, __HIP_MEMORY_SCOPE_AGENT); }
; #define GSYNC xcd_barrier(bar, xcc, nloc, nx)
; DEVI void xcd_barrier(unsigned* bar, unsigned x, unsigned nloc, unsigned nx) {
;   asm volatile("s_waitcnt vmcnt(0)" ::: "memory");
;   __syncthreads();
;   if (threadIdx.x == 0) {
;     __builtin_amdgcn_s_waitcnt(0);
;     const unsigned old = xb_add(&bar[XB_XSUB(x)], 1u);
;     const unsigned gen = old / nloc;
;     if (old + 1u == (gen + 1u) * nloc) {
;       __builtin_amdgcn_fence(__ATOMIC_RELEASE, "agent");
;       asm volatile("s_waitcnt vmcnt(0)" ::: "memory");
;       const unsigned og = xb_add(&bar[XB_TOP], 1u);
;       const unsigned tg = og / nx;
;       if (og + 1u == (tg + 1u) * nx) xb_add(&bar[XB_TOPGEN], 1u);
; __global__ void __launch_bounds__(256, 2) fwd_megakernel(Params P) {
;     ...
;       if (!(l == 1 && it == 2)) GSYNC;
.Ltb_skip_d:
.LBB0_298:
	s_xor_b64 s[42:43], s[72:73], -1
	s_mov_b64 s[72:73], 0
	s_mov_b64 s[40:41], -1
	s_and_b64 vcc, exec, s[42:43]
	s_cbranch_vccz .Lsplit_latch
	v_readlane_b32 s4, v252, 34
	s_cmp_lg_u32 s0, s0
	v_readlane_b32 s5, v252, 35
	s_cselect_b64 s[40:41], -1, 0
	s_xor_b64 s[42:43], s[4:5], -1
	s_or_b64 s[40:41], s[42:43], s[40:41]
	s_and_b64 vcc, exec, s[40:41]
	v_readlane_b32 s74, v252, 32
	s_cbranch_vccz .LBB0_338
	s_waitcnt vmcnt(0)
	s_barrier
	s_mov_b64 s[40:41], exec
	v_readlane_b32 s42, v253, 4
	v_readlane_b32 s43, v253, 5
	s_and_b64 s[42:43], s[40:41], s[42:43]
	s_mov_b64 exec, s[42:43]
	s_cbranch_execz .LBB0_337
	s_mov_b64 s[42:43], exec
	v_mbcnt_lo_u32_b32 v0, s42, 0
	v_mbcnt_hi_u32_b32 v0, s43, v0
	v_cmp_eq_u32_e32 vcc, 0, v0
	s_waitcnt vmcnt(0) expcnt(0) lgkmcnt(0)
	s_and_saveexec_b64 s[44:45], vcc
	s_cbranch_execz .LBB0_303
	s_bcnt1_i32_b64 s1, s[42:43]
	v_readlane_b32 s4, v253, 30
	v_mov_b32_e32 v1, s1
	v_readlane_b32 s5, v253, 31
	s_nop 4
	global_atomic_add v1, v89, v1, s[4:5] sc0

; DEVI char* wsp(const Params& P, size_t off) { asm volatile("" : "+s"(off)); return P.ws + off; }
; DEVI int ltid() { int t = threadIdx.x; asm volatile("" : "+v"(t)); return t; }
; DEVI void convert_chunk_fp8(const float* __restrict__ src, unsigned char* __restrict__ dst, float scale, int tid) {
;   int o = tid * 16;
;   uint4 r;
;   unsigned rr[4];
; #pragma unroll
;   for (int q = 0; q < 4; ++q) {
;     float4 a = *reinterpret_cast<const float4*>(src + o + q * 4);
;     int p = __builtin_amdgcn_cvt_pk_fp8_f32(a.x * scale, a.y * scale, 0, false);
;     p = __builtin_amdgcn_cvt_pk_fp8_f32(a.z * scale, a.w * scale, p, true);
;     rr[q] = (unsigned)p;
;   }
;   r = make_uint4(rr[0], rr[1], rr[2], rr[3]);
;   *reinterpret_cast<uint4*>(dst + o) = r;
; }
; DEVI void phase6(const Params& P, int l, int pass, char* smem) {
;   const int tid = ltid();
;   const int ntok = pass ? 8192 : 8448;
;   const int nM = ntok / 128, nN = 8;
;   const bfu* Z = (const bfu*)wsp(P, O_Z);
;   bfu* M = (bfu*)wsp(P, O_CB);
;   for (int id = blockIdx.x; id < nM * nN; id += gridDim.x) {
;     int pm, pn; tile_rc_m(id, nM, nN, pm, pn);
;     float* macc = (float*)wsp(P, O_AU);
;     p6_branch<2, 1, 1>(P, pm, pn, macc, smem, tid);
.LBB0_728:
	s_or_b64 exec, exec, s[26:27]
	s_barrier
	v_readlane_b32 s60, v252, 36
	s_cmp_lg_u32 s0, 1
	s_cbranch_scc1 .Ltb_skip_a
	s_cmp_lg_u32 s60, 0
	s_cbranch_scc1 .Ltb_skip_a
	v_readlane_b32 s60, v252, 32
	s_cmpk_lt_u32 s60, 0x100
	s_cbranch_scc0 .Ltb_skip_a
	v_readlane_b32 s54, v253, 22
	v_readlane_b32 s55, v253, 23
	v_readlane_b32 s56, v253, 24
	v_readlane_b32 s57, v253, 25
	s_lshl_b32 s61, s0, 26
	s_add_u32 s54, s54, s61
	s_addc_u32 s55, s55, 0
	s_add_u32 s56, s56, s61
	s_addc_u32 s57, s57, 0
	v_lshlrev_b32_e32 v248, 6, v93
	v_lshlrev_b32_e32 v250, 4, v93
	v_mov_b32_e32 v251, 0
	v_lshl_add_u64 v[250:251], v[64:65], 0, v[250:251]

; DEVI char* wsp(const Params& P, size_t off) { asm volatile("" : "+s"(off)); return P.ws + off; }
; DEVI void convert_chunk_fp8(const float* __restrict__ src, unsigned char* __restrict__ dst, float scale, int tid) {
;   int o = tid * 16;
;   uint4 r;
;   unsigned rr[4];
; #pragma unroll
;   for (int q = 0; q < 4; ++q) {
;     float4 a = *reinterpret_cast<const float4*>(src + o + q * 4);
;     int p = __builtin_amdgcn_cvt_pk_fp8_f32(a.x * scale, a.y * scale, 0, false);
;     p = __builtin_amdgcn_cvt_pk_fp8_f32(a.z * scale, a.w * scale, p, true);
;     rr[q] = (unsigned)p;
;   }
;   r = make_uint4(rr[0], rr[1], rr[2], rr[3]);
;   *reinterpret_cast<uint4*>(dst + o) = r;
; }
; DEVI void phase6(const Params& P, int l, int pass, char* smem) {
;     ...
;   for (int id = blockIdx.x; id < nM * nN; id += gridDim.x) {
;     int pm, pn; tile_rc_m(id, nM, nN, pm, pn);
;     float* macc = (float*)wsp(P, O_AU);
;     p6_branch<2, 1, 1>(P, pm, pn, macc, smem, tid);
;     p6_branch<1, 2, 0>(P, pm, pn, macc, smem, tid);
;   }
; }
.LBB0_743:
	v_readlane_b32 s60, v252, 36
	s_cmp_lg_u32 s0, 1
	s_cbranch_scc1 .Ltb_skip_b
	s_cmp_lg_u32 s60, 0
	s_cbranch_scc1 .Ltb_skip_b
	v_readlane_b32 s60, v252, 32
	s_cmpk_lt_u32 s60, 0x100
	s_cbranch_scc1 .Ltb_skip_b
	v_readlane_b32 s54, v253, 22
	v_readlane_b32 s55, v253, 23
	v_readlane_b32 s56, v253, 24
	v_readlane_b32 s57, v253, 25
	s_lshl_b32 s61, s0, 26
	s_add_u32 s54, s54, s61
	s_addc_u32 s55, s55, 0
	s_add_u32 s56, s56, s61
	s_addc_u32 s57, s57, 0
	v_lshlrev_b32_e32 v248, 6, v93
	v_lshlrev_b32_e32 v250, 4, v93
	v_mov_b32_e32 v251, 0
	v_lshl_add_u64 v[250:251], v[64:65], 0, v[250:251]
